# MLA latent units: V tile LDS row pitch 144->192 B so ds_read_b64_tr_b16 lane groups are bank-conflict free
# speedup vs baseline: 1.0032x; 1.0032x over previous
.LBB0_530:
	s_or_b64 exec, exec, s[6:7]
	global_load_dwordx4 v[118:121], v[6:7], off offset:128
	v_and_b32_e32 v1, 16, v149
	v_lshlrev_b32_e32 v148, 2, v9
	v_lshlrev_b32_e32 v2, 2, v149
	s_waitcnt lgkmcnt(0)
	s_barrier
	v_and_or_b32 v0, v0, 3, v148
	v_and_or_b32 v1, v2, 12, v1
	v_lshlrev_b32_e32 v155, 6, v153
	v_mul_u32_u24_e32 v0, 0xc0, v0
	v_lshlrev_b32_e32 v1, 1, v1
	v_mul_u32_u24_e32 v2, 0xd0, v8
	v_mul_u32_u24_e32 v156, 0xc0, v153
	s_cmpk_lt_u32 s10, 0x100
	v_add3_u32 v149, 0, v4, v2
	v_add3_u32 v97, v1, v0, 0
	v_mul_lo_u32 v151, v152, s81
	v_add_u32_e32 v135, v156, v134
	s_mov_b64 s[6:7], -1
	s_nop 0
	ds_read_b128 v[0:3], v149 offset:6720
	ds_read_b128 v[4:7], v149 offset:6688
	ds_read_b128 v[8:11], v149
	ds_read_b128 v[46:49], v149 offset:32
	ds_read_b128 v[50:53], v149 offset:64
	ds_read_b128 v[54:57], v149 offset:6656
	v_readlane_b32 s40, v254, 47
	s_mov_b32 s12, s40
	v_readlane_b32 s41, v254, 48
	v_readlane_b32 s42, v254, 49
	v_readlane_b32 s43, v254, 50
	v_readlane_b32 s44, v254, 51
	v_readlane_b32 s45, v254, 52
	v_readlane_b32 s46, v254, 53
	v_readlane_b32 s47, v254, 54
	v_readlane_b32 s48, v254, 55
	v_readlane_b32 s49, v254, 56
	v_readlane_b32 s50, v254, 57
	v_readlane_b32 s51, v254, 58
	v_readlane_b32 s52, v254, 59
	v_readlane_b32 s53, v254, 60
	v_readlane_b32 s54, v254, 61
	v_readlane_b32 s55, v254, 62
	v_writelane_b32 v254, s12, 47
	s_mov_b32 s41, s40
	s_mov_b32 s42, s40
	v_writelane_b32 v254, s13, 48
	v_writelane_b32 v254, s14, 49
	v_writelane_b32 v254, s15, 50
	v_writelane_b32 v254, s16, 51
	v_writelane_b32 v254, s17, 52
	s_mov_b32 s43, s40
	s_mov_b32 s44, s40
	s_mov_b32 s45, s40
	s_mov_b32 s46, s40
	s_mov_b32 s47, s40
	s_mov_b32 s48, s40
	s_mov_b32 s49, s40
	s_mov_b32 s50, s40
	s_mov_b32 s51, s40
	s_mov_b32 s52, s40
	s_mov_b32 s53, s40
	s_mov_b32 s54, s40
	s_mov_b32 s55, s40
	v_writelane_b32 v254, s18, 53
	v_mov_b64_e32 v[30:31], s[40:41]
	v_writelane_b32 v254, s19, 54
	v_mov_b64_e32 v[32:33], s[42:43]
	v_mov_b64_e32 v[34:35], s[44:45]
	v_mov_b64_e32 v[36:37], s[46:47]
	v_mov_b64_e32 v[38:39], s[48:49]
	v_mov_b64_e32 v[40:41], s[50:51]
	v_mov_b64_e32 v[42:43], s[52:53]
	v_mov_b64_e32 v[44:45], s[54:55]
	v_writelane_b32 v254, s20, 55
	v_writelane_b32 v254, s21, 56
	s_waitcnt lgkmcnt(3)
	v_mfma_f32_32x32x16_bf16 v[14:29], v[8:11], v[106:109], v[30:45]
	v_writelane_b32 v254, s22, 57
	v_writelane_b32 v254, s23, 58
	v_writelane_b32 v254, s24, 59
	v_writelane_b32 v254, s25, 60
	v_writelane_b32 v254, s26, 61
	v_writelane_b32 v254, s27, 62
	s_waitcnt lgkmcnt(0)
	v_mfma_f32_32x32x16_bf16 v[30:45], v[54:57], v[106:109], v[30:45]
	ds_read_b128 v[8:11], v149 offset:96
	ds_read_b128 v[54:57], v149 offset:6752
	v_mfma_f32_32x32x16_bf16 v[14:29], v[46:49], v[102:105], v[14:29]
	v_mfma_f32_32x32x16_bf16 v[30:45], v[4:7], v[102:105], v[30:45]
	ds_read_b128 v[4:7], v149 offset:128
	ds_read_b128 v[46:49], v149 offset:6784
	v_mfma_f32_32x32x16_bf16 v[14:29], v[50:53], v[92:95], v[14:29]
	v_mfma_f32_32x32x16_bf16 v[30:45], v[0:3], v[92:95], v[30:45]
	ds_read_b128 v[0:3], v149 offset:160
	ds_read_b128 v[50:53], v149 offset:6816
	s_waitcnt lgkmcnt(5)
	v_mfma_f32_32x32x16_bf16 v[14:29], v[8:11], v[88:91], v[14:29]
	s_waitcnt lgkmcnt(4)
	v_mfma_f32_32x32x16_bf16 v[30:45], v[54:57], v[88:91], v[30:45]
	s_waitcnt lgkmcnt(3)
	v_mfma_f32_32x32x16_bf16 v[14:29], v[4:7], v[84:87], v[14:29]
	s_waitcnt lgkmcnt(2)
	v_mfma_f32_32x32x16_bf16 v[30:45], v[46:49], v[84:87], v[30:45]
	s_waitcnt lgkmcnt(1)
	v_mfma_f32_32x32x16_bf16 v[14:29], v[0:3], v[80:83], v[14:29]
	s_waitcnt lgkmcnt(0)
	v_mfma_f32_32x32x16_bf16 v[30:45], v[50:53], v[80:83], v[30:45]
	s_waitcnt vmcnt(1)
	ds_write_b128 v154, v[114:117] offset:13312
	s_and_saveexec_b64 s[6:7], s[38:39]
	v_add3_u32 v0, 0, v151, v136
	ds_write_b128 v0, v[110:113] offset:13440
	s_or_b64 exec, exec, s[6:7]
	s_add_i32 s1, s9, 0x8080
	v_add_u32_e32 v0, s1, v153
	v_ashrrev_i32_e32 v1, 31, v0
	v_lshlrev_b64 v[0:1], 10, v[0:1]
	v_lshl_add_u64 v[0:1], s[92:93], 0, v[0:1]
	v_lshl_add_u64 v[0:1], v[0:1], 0, s[68:69]
	v_lshl_add_u64 v[0:1], v[0:1], 0, v[98:99]
	global_load_dwordx4 v[126:129], v[0:1], off
	v_mov_b64_e32 v[124:125], v[112:113]
	v_mov_b64_e32 v[122:123], v[110:111]
	s_waitcnt vmcnt(1)
	ds_write_b128 v135, v[118:121] offset:26624
	s_and_saveexec_b64 s[6:7], s[38:39]
	s_cbranch_execz .LBB0_535
	v_add_u32_e32 v0, s1, v152
	v_ashrrev_i32_e32 v1, 31, v0
	v_lshlrev_b64 v[0:1], 6, v[0:1]
	v_lshl_add_u64 v[0:1], s[26:27], 0, v[0:1]
	v_lshl_add_u64 v[0:1], v[100:101], 1, v[0:1]
	global_load_dwordx4 v[122:125], v[0:1], off
.LBB0_535:
	s_or_b64 exec, exec, s[6:7]
	v_max3_f32 v1, v14, v15, v30
	v_max3_f32 v2, v16, v17, v31
	v_add_u32_e32 v142, s9, v153
	v_max3_f32 v1, v1, v32, v33
	v_max3_f32 v2, v2, v20, v21
	v_cmp_lt_i32_e32 vcc, v232, v226
	v_max3_f32 v1, v1, v18, v19
	v_max3_f32 v2, v2, v36, v37
	v_add_u32_e32 v0, 0x8040, v142
	v_max3_f32 v1, v1, v34, v35
	v_max3_f32 v2, v2, v24, v25
	s_nop 0
	v_max3_f32 v1, v1, v22, v23
	v_max3_f32 v2, v2, v40, v41
	s_nop 0
	v_max3_f32 v1, v1, v38, v39
	v_max3_f32 v2, v2, v28, v29
	s_nop 0
	v_max3_f32 v1, v1, v26, v27
	v_max3_f32 v2, v2, v44, v45
	s_nop 0
	v_max3_f32 v1, v1, v42, v43
	s_nop 0
	v_max3_f32 v2, v1, v2, v2
	v_cndmask_b32_e32 v1, v225, v232, vcc
	v_lshlrev_b32_e32 v137, 2, v1
	v_ashrrev_i32_e32 v1, 31, v0
	v_lshlrev_b64 v[0:1], 10, v[0:1]
	v_lshl_add_u64 v[0:1], s[92:93], 0, v[0:1]
	v_lshl_add_u64 v[0:1], v[0:1], 0, s[68:69]
	v_lshl_add_u64 v[0:1], v[0:1], 0, v[98:99]
	global_load_dwordx4 v[130:133], v[0:1], off offset:128
	ds_bpermute_b32 v3, v137, v2
	s_waitcnt lgkmcnt(0)
	v_max3_f32 v47, v2, v3, v2
	s_waitcnt lgkmcnt(0)
	s_barrier
	s_nop 0
	v_sub_f32_e32 v30, v30, v47
	v_sub_f32_e32 v14, v14, v47
	v_sub_f32_e32 v31, v31, v47
	v_sub_f32_e32 v15, v15, v47
	v_exp_f32_e32 v61, v14
	v_exp_f32_e32 v62, v30
	v_sub_f32_e32 v49, v34, v47
	v_sub_f32_e32 v34, v16, v47
	v_exp_f32_e32 v16, v15
	v_exp_f32_e32 v30, v31
	v_sub_f32_e32 v50, v35, v47
	v_sub_f32_e32 v35, v17, v47
	v_add_f32_e32 v31, v62, v61
	v_mov_b32_e32 v17, v99
	v_sub_f32_e32 v46, v32, v47
	v_pk_add_f32 v[14:15], v[30:31], v[16:17]
	v_sub_f32_e32 v48, v33, v47
	v_pk_add_f32 v[32:33], v[14:15], v[14:15] op_sel_hi:[0,1]
	v_exp_f32_e32 v17, v34
	v_exp_f32_e32 v31, v46
	v_exp_f32_e32 v32, v35
	v_exp_f32_e32 v34, v48
	v_sub_f32_e32 v51, v36, v47
	v_add_f32_e32 v35, v31, v17
	v_sub_f32_e32 v36, v18, v47
	v_pk_add_f32 v[14:15], v[34:35], v[32:33]
	v_sub_f32_e32 v52, v37, v47
	v_sub_f32_e32 v37, v19, v47
	v_pk_add_f32 v[18:19], v[14:15], v[14:15] op_sel_hi:[0,1]
	v_exp_f32_e32 v33, v36
	v_exp_f32_e32 v35, v49
	v_exp_f32_e32 v18, v37
	v_exp_f32_e32 v36, v50
	v_sub_f32_e32 v53, v38, v47
	v_add_f32_e32 v37, v35, v33
	v_sub_f32_e32 v38, v20, v47
	v_pk_add_f32 v[14:15], v[36:37], v[18:19]
	v_sub_f32_e32 v54, v39, v47
	v_sub_f32_e32 v39, v21, v47
	v_pk_add_f32 v[20:21], v[14:15], v[14:15] op_sel_hi:[0,1]
	v_exp_f32_e32 v19, v38
	v_exp_f32_e32 v37, v51
	v_exp_f32_e32 v20, v39
	v_exp_f32_e32 v38, v52
	v_sub_f32_e32 v55, v40, v47
	v_add_f32_e32 v39, v37, v19
	v_sub_f32_e32 v40, v22, v47
	v_pk_add_f32 v[14:15], v[38:39], v[20:21]
	v_sub_f32_e32 v56, v41, v47
	v_sub_f32_e32 v41, v23, v47
	v_pk_add_f32 v[22:23], v[14:15], v[14:15] op_sel_hi:[0,1]
	v_exp_f32_e32 v21, v40
	v_exp_f32_e32 v39, v53
	v_exp_f32_e32 v22, v41
	v_exp_f32_e32 v40, v54
	v_sub_f32_e32 v57, v42, v47
	v_add_f32_e32 v41, v39, v21
	v_sub_f32_e32 v42, v24, v47
	v_pk_add_f32 v[14:15], v[40:41], v[22:23]
	v_sub_f32_e32 v58, v43, v47
	v_sub_f32_e32 v43, v25, v47
	v_pk_add_f32 v[24:25], v[14:15], v[14:15] op_sel_hi:[0,1]
	v_exp_f32_e32 v23, v42
	v_exp_f32_e32 v41, v55
	v_exp_f32_e32 v24, v43
	v_exp_f32_e32 v42, v56
	v_sub_f32_e32 v59, v44, v47
	v_add_f32_e32 v43, v41, v23
	v_sub_f32_e32 v44, v26, v47
	v_pk_add_f32 v[14:15], v[42:43], v[24:25]
	v_sub_f32_e32 v60, v45, v47
	v_sub_f32_e32 v45, v27, v47
	v_pk_add_f32 v[26:27], v[14:15], v[14:15] op_sel_hi:[0,1]
	v_exp_f32_e32 v25, v44
	v_exp_f32_e32 v43, v57
	v_exp_f32_e32 v26, v45
	v_exp_f32_e32 v44, v58
	v_sub_f32_e32 v46, v28, v47
	v_add_f32_e32 v45, v43, v25
	v_sub_f32_e32 v48, v29, v47
	v_pk_add_f32 v[14:15], v[44:45], v[26:27]
	v_exp_f32_e32 v27, v46
	v_pk_add_f32 v[28:29], v[14:15], v[14:15] op_sel_hi:[0,1]
	v_exp_f32_e32 v45, v59
	v_exp_f32_e32 v28, v48
	v_exp_f32_e32 v48, v60
	v_cvt_pk_bf16_f32 v144, v61, v16
	v_add_f32_e32 v49, v45, v27
	v_cvt_pk_bf16_f32 v145, v17, v32
	v_pk_add_f32 v[50:51], v[48:49], v[28:29]
	v_cvt_pk_bf16_f32 v146, v33, v18
	v_cvt_pk_bf16_f32 v147, v19, v20
	v_cvt_pk_bf16_f32 v158, v21, v22
	v_cvt_pk_bf16_f32 v159, v23, v24
	v_cvt_pk_bf16_f32 v160, v25, v26
	v_cvt_pk_bf16_f32 v161, v27, v28
	v_cvt_pk_bf16_f32 v162, v62, v30
	v_cvt_pk_bf16_f32 v163, v31, v34
	ds_read_b128 v[16:19], v149 offset:13312
	ds_read_b128 v[20:23], v149 offset:13344
	ds_read_b128 v[24:27], v149 offset:19968
	ds_read_b128 v[28:31], v149 offset:13376
	ds_read_b128 v[170:173], v149 offset:20000
	ds_read_b128 v[174:177], v149 offset:20032
	v_exp_f32_e64 v2, -v47
	v_pk_add_f32 v[50:51], v[50:51], v[50:51] op_sel:[0,1] op_sel_hi:[1,0]
	v_cvt_pk_bf16_f32 v164, v35, v36
	v_mov_b32_e32 v51, v99
	v_mul_f32_e32 v0, 0, v2
	v_mov_b32_e32 v46, v0
	v_pk_add_f32 v[138:139], v[46:47], v[50:51]
	v_mov_b32_e32 v1, v0
	v_mov_b32_e32 v2, v0
	v_mov_b32_e32 v3, v0
	v_mov_b32_e32 v4, v0
	v_mov_b32_e32 v5, v0
	v_mov_b32_e32 v6, v0
	v_mov_b32_e32 v7, v0
	v_mov_b32_e32 v8, v0
	v_mov_b32_e32 v9, v0
	v_mov_b32_e32 v10, v0
	v_mov_b32_e32 v11, v0
	v_mov_b32_e32 v12, v0
	v_mov_b32_e32 v13, v0
	v_mov_b32_e32 v14, v0
	v_mov_b32_e32 v15, v0
	v_xor_b32_e32 v32, 0x80000000, v139
	v_cvt_pk_bf16_f32 v165, v37, v38
	v_cvt_pk_bf16_f32 v166, v39, v40
	v_cvt_pk_bf16_f32 v167, v41, v42
	v_cvt_pk_bf16_f32 v168, v43, v44
	v_cvt_pk_bf16_f32 v169, v45, v48
	v_mov_b32_e32 v33, v32
	v_mov_b32_e32 v34, v32
	v_mov_b32_e32 v35, v32
	v_mov_b32_e32 v36, v32
	v_mov_b32_e32 v37, v32
	v_mov_b32_e32 v38, v32
	v_mov_b32_e32 v39, v32
	v_mov_b32_e32 v40, v32
	v_mov_b32_e32 v41, v32
	v_mov_b32_e32 v42, v32
	v_mov_b32_e32 v43, v32
	v_mov_b32_e32 v44, v32
	v_mov_b32_e32 v45, v32
	v_mov_b32_e32 v46, v32
	v_mov_b32_e32 v47, v32
	v_mov_b64_e32 v[78:79], v[46:47]
	v_mov_b64_e32 v[76:77], v[44:45]
	v_mov_b64_e32 v[74:75], v[42:43]
	v_mov_b64_e32 v[72:73], v[40:41]
	v_mov_b64_e32 v[70:71], v[38:39]
	v_mov_b64_e32 v[68:69], v[36:37]
	v_mov_b64_e32 v[66:67], v[34:35]
	v_mov_b64_e32 v[64:65], v[32:33]
	s_waitcnt lgkmcnt(5)
	v_mfma_f32_32x32x16_bf16 v[48:63], v[16:19], v[106:109], v[32:47]
	s_waitcnt lgkmcnt(3)
	v_mfma_f32_32x32x16_bf16 v[64:79], v[24:27], v[106:109], v[64:79]
	ds_read_b128 v[16:19], v149 offset:13408
	ds_read_b128 v[24:27], v149 offset:20064
	v_mfma_f32_32x32x16_bf16 v[48:63], v[20:23], v[102:105], v[48:63]
	s_waitcnt lgkmcnt(3)
	v_mfma_f32_32x32x16_bf16 v[64:79], v[170:173], v[102:105], v[64:79]
	ds_read_b128 v[20:23], v149 offset:13440
	ds_read_b128 v[34:37], v149 offset:20096
	v_mfma_f32_32x32x16_bf16 v[48:63], v[28:31], v[92:95], v[48:63]
	s_waitcnt lgkmcnt(4)
	v_mfma_f32_32x32x16_bf16 v[64:79], v[174:177], v[92:95], v[64:79]
	ds_read_b128 v[28:31], v149 offset:13472
	ds_read_b128 v[38:41], v149 offset:20128
	s_waitcnt lgkmcnt(5)
	v_mfma_f32_32x32x16_bf16 v[48:63], v[16:19], v[88:91], v[48:63]
	s_waitcnt lgkmcnt(4)
	v_mfma_f32_32x32x16_bf16 v[64:79], v[24:27], v[88:91], v[64:79]
	ds_read_b64_tr_b16 v[42:43], v97 offset:26624
	ds_read_b64_tr_b16 v[44:45], v97 offset:28160
	ds_read_b64_tr_b16 v[172:173], v97 offset:28224
	ds_read_b64_tr_b16 v[170:171], v97 offset:26688
	s_waitcnt lgkmcnt(7)
	v_mfma_f32_32x32x16_bf16 v[48:63], v[20:23], v[84:87], v[48:63]
	s_waitcnt lgkmcnt(6)
	v_mfma_f32_32x32x16_bf16 v[64:79], v[34:37], v[84:87], v[64:79]
	ds_read_b64_tr_b16 v[34:35], v97 offset:29696
	ds_read_b64_tr_b16 v[36:37], v97 offset:31232
	ds_read_b64_tr_b16 v[176:177], v97 offset:31296
	ds_read_b64_tr_b16 v[174:175], v97 offset:29760
	s_waitcnt lgkmcnt(9)
	v_mfma_f32_32x32x16_bf16 v[48:63], v[28:31], v[80:83], v[48:63]
	s_waitcnt lgkmcnt(8)
	v_mfma_f32_32x32x16_bf16 v[64:79], v[38:41], v[80:83], v[64:79]
	ds_read_b64_tr_b16 v[38:39], v97 offset:32768
	ds_read_b64_tr_b16 v[40:41], v97 offset:34304
	ds_read_b64_tr_b16 v[190:191], v97 offset:34368
	ds_read_b64_tr_b16 v[188:189], v97 offset:32832
	s_waitcnt lgkmcnt(10)
	v_mfma_f32_32x32x16_bf16 v[16:31], v[42:45], v[144:147], v[0:15]
	s_waitcnt lgkmcnt(8)
	v_mfma_f32_32x32x16_bf16 v[0:15], v[170:173], v[144:147], v[0:15]
	ds_read_b64_tr_b16 v[42:43], v97 offset:35840
	ds_read_b64_tr_b16 v[44:45], v97 offset:37376
	ds_read_b64_tr_b16 v[146:147], v97 offset:37440
	ds_read_b64_tr_b16 v[144:145], v97 offset:35904
	s_waitcnt lgkmcnt(10)
	v_mfma_f32_32x32x16_bf16 v[16:31], v[34:37], v[158:161], v[16:31]
	s_waitcnt lgkmcnt(8)
	v_mfma_f32_32x32x16_bf16 v[0:15], v[174:177], v[158:161], v[0:15]
	s_waitcnt lgkmcnt(6)
	v_mfma_f32_32x32x16_bf16 v[16:31], v[38:41], v[162:165], v[16:31]
	s_waitcnt lgkmcnt(4)
	v_mfma_f32_32x32x16_bf16 v[0:15], v[188:191], v[162:165], v[0:15]
	s_waitcnt lgkmcnt(2)
	v_mfma_f32_32x32x16_bf16 v[16:31], v[42:45], v[166:169], v[16:31]
	s_waitcnt lgkmcnt(0)
	v_mfma_f32_32x32x16_bf16 v[0:15], v[144:147], v[166:169], v[0:15]
	s_waitcnt vmcnt(1)
	ds_write_b128 v154, v[126:129]
	s_and_saveexec_b64 s[6:7], s[38:39]
	v_add3_u32 v33, 0, v151, v136
	ds_write_b128 v33, v[122:125] offset:128
	s_or_b64 exec, exec, s[6:7]
	s_add_i32 s1, s9, 0x80c0
	v_add_u32_e32 v34, s1, v153
	v_ashrrev_i32_e32 v35, 31, v34
	v_lshlrev_b64 v[34:35], 10, v[34:35]
	v_lshl_add_u64 v[34:35], s[92:93], 0, v[34:35]
	v_lshl_add_u64 v[34:35], v[34:35], 0, s[68:69]
	v_lshl_add_u64 v[34:35], v[34:35], 0, v[98:99]
	global_load_dwordx4 v[126:129], v[34:35], off
	s_waitcnt vmcnt(1)
	ds_write_b128 v135, v[130:133] offset:38912
	s_and_saveexec_b64 s[6:7], s[38:39]
	s_cbranch_execz .LBB0_539
	v_add_u32_e32 v34, s1, v152
	v_ashrrev_i32_e32 v35, 31, v34
	v_lshlrev_b64 v[34:35], 6, v[34:35]
	v_lshl_add_u64 v[34:35], s[26:27], 0, v[34:35]
	v_lshl_add_u64 v[34:35], v[100:101], 1, v[34:35]
	global_load_dwordx4 v[122:125], v[34:35], off

.LBB0_541:
	ds_read_b128 v[188:191], v149
	ds_read_b128 v[192:195], v149 offset:32
	ds_read_b128 v[196:199], v149 offset:6656
	ds_read_b128 v[200:203], v149 offset:64
	ds_read_b128 v[204:207], v149 offset:6688
	ds_read_b128 v[208:211], v149 offset:6720
	v_exp_f32_e32 v143, v48
	v_exp_f32_e32 v144, v64
	v_exp_f32_e32 v64, v49
	v_exp_f32_e32 v145, v65
	v_exp_f32_e32 v65, v50
	v_exp_f32_e32 v146, v66
	v_exp_f32_e32 v66, v51
	v_exp_f32_e32 v147, v67
	v_exp_f32_e32 v67, v52
	v_exp_f32_e32 v157, v68
	v_exp_f32_e32 v68, v53
	v_exp_f32_e32 v158, v69
	v_exp_f32_e32 v69, v54
	v_exp_f32_e32 v159, v70
	v_exp_f32_e32 v70, v55
	v_exp_f32_e32 v160, v71
	v_exp_f32_e32 v71, v56
	v_exp_f32_e32 v161, v72
	v_exp_f32_e32 v72, v57
	v_exp_f32_e32 v162, v73
	v_exp_f32_e32 v73, v58
	v_exp_f32_e32 v163, v74
	v_exp_f32_e32 v74, v59
	v_exp_f32_e32 v164, v75
	v_exp_f32_e32 v75, v60
	v_exp_f32_e32 v165, v76
	v_exp_f32_e32 v76, v61
	v_exp_f32_e32 v166, v77
	v_exp_f32_e32 v77, v62
	v_exp_f32_e32 v167, v78
	v_exp_f32_e32 v78, v63
	v_exp_f32_e32 v79, v79
	v_mov_b32_e32 v33, v32
	v_mov_b32_e32 v34, v32
	v_mov_b32_e32 v35, v32
	v_mov_b32_e32 v36, v32
	v_mov_b32_e32 v37, v32
	v_mov_b32_e32 v38, v32
	v_mov_b32_e32 v39, v32
	v_mov_b32_e32 v40, v32
	v_mov_b32_e32 v41, v32
	v_mov_b32_e32 v42, v32
	v_mov_b32_e32 v43, v32
	v_mov_b32_e32 v44, v32
	v_mov_b32_e32 v45, v32
	v_mov_b32_e32 v46, v32
	v_mov_b32_e32 v47, v32
	v_cvt_pk_bf16_f32 v168, v143, v64
	v_cvt_pk_bf16_f32 v169, v65, v66
	v_cvt_pk_bf16_f32 v170, v67, v68
	v_cvt_pk_bf16_f32 v171, v69, v70
	v_cvt_pk_bf16_f32 v172, v71, v72
	v_cvt_pk_bf16_f32 v173, v73, v74
	v_cvt_pk_bf16_f32 v174, v75, v76
	v_cvt_pk_bf16_f32 v175, v77, v78
	v_cvt_pk_bf16_f32 v176, v144, v145
	v_cvt_pk_bf16_f32 v177, v146, v147
	v_cvt_pk_bf16_f32 v178, v157, v158
	v_cvt_pk_bf16_f32 v179, v159, v160
	v_cvt_pk_bf16_f32 v212, v161, v162
	v_cvt_pk_bf16_f32 v213, v163, v164
	v_cvt_pk_bf16_f32 v214, v165, v166
	v_cvt_pk_bf16_f32 v215, v167, v79
	s_waitcnt lgkmcnt(5)
	v_mfma_f32_32x32x16_bf16 v[48:63], v[188:191], v[106:109], v[32:47]
	s_waitcnt lgkmcnt(3)
	v_mfma_f32_32x32x16_bf16 v[32:47], v[196:199], v[106:109], v[32:47]
	ds_read_b128 v[188:191], v149 offset:96
	ds_read_b128 v[196:199], v149 offset:6752
	v_mfma_f32_32x32x16_bf16 v[48:63], v[192:195], v[102:105], v[48:63]
	s_waitcnt lgkmcnt(3)
	v_mfma_f32_32x32x16_bf16 v[32:47], v[204:207], v[102:105], v[32:47]
	ds_read_b128 v[192:195], v149 offset:128
	ds_read_b128 v[204:207], v149 offset:6784
	v_mfma_f32_32x32x16_bf16 v[48:63], v[200:203], v[92:95], v[48:63]
	s_waitcnt lgkmcnt(4)
	v_mfma_f32_32x32x16_bf16 v[32:47], v[208:211], v[92:95], v[32:47]
	ds_read_b128 v[200:203], v149 offset:160
	ds_read_b128 v[208:211], v149 offset:6816
	s_waitcnt lgkmcnt(5)
	v_mfma_f32_32x32x16_bf16 v[48:63], v[188:191], v[88:91], v[48:63]
	s_waitcnt lgkmcnt(4)
	v_mfma_f32_32x32x16_bf16 v[32:47], v[196:199], v[88:91], v[32:47]
	ds_read_b64_tr_b16 v[188:189], v97 offset:38912
	ds_read_b64_tr_b16 v[190:191], v97 offset:40448
	ds_read_b64_tr_b16 v[198:199], v97 offset:40512
	ds_read_b64_tr_b16 v[196:197], v97 offset:38976
	s_waitcnt lgkmcnt(7)
	v_mfma_f32_32x32x16_bf16 v[48:63], v[192:195], v[84:87], v[48:63]
	s_waitcnt lgkmcnt(6)
	v_mfma_f32_32x32x16_bf16 v[32:47], v[204:207], v[84:87], v[32:47]
	ds_read_b64_tr_b16 v[192:193], v97 offset:41984
	ds_read_b64_tr_b16 v[194:195], v97 offset:43520
	ds_read_b64_tr_b16 v[206:207], v97 offset:43584
	ds_read_b64_tr_b16 v[204:205], v97 offset:42048
	s_waitcnt lgkmcnt(9)
	v_mfma_f32_32x32x16_bf16 v[48:63], v[200:203], v[80:83], v[48:63]
	s_waitcnt lgkmcnt(8)
	v_mfma_f32_32x32x16_bf16 v[32:47], v[208:211], v[80:83], v[32:47]
	ds_read_b64_tr_b16 v[200:201], v97 offset:45056
	ds_read_b64_tr_b16 v[202:203], v97 offset:46592
	ds_read_b64_tr_b16 v[210:211], v97 offset:46656
	ds_read_b64_tr_b16 v[208:209], v97 offset:45120
	s_waitcnt lgkmcnt(10)
	v_mfma_f32_32x32x16_bf16 v[16:31], v[188:191], v[168:171], v[16:31]
	s_waitcnt lgkmcnt(8)
	v_mfma_f32_32x32x16_bf16 v[0:15], v[196:199], v[168:171], v[0:15]
	ds_read_b64_tr_b16 v[168:169], v97 offset:48128
	ds_read_b64_tr_b16 v[170:171], v97 offset:49664
	ds_read_b64_tr_b16 v[190:191], v97 offset:49728
	ds_read_b64_tr_b16 v[188:189], v97 offset:48192
	s_waitcnt lgkmcnt(10)
	v_mfma_f32_32x32x16_bf16 v[16:31], v[192:195], v[172:175], v[16:31]
	s_waitcnt lgkmcnt(8)
	v_mfma_f32_32x32x16_bf16 v[0:15], v[204:207], v[172:175], v[0:15]
	s_waitcnt lgkmcnt(6)
	v_mfma_f32_32x32x16_bf16 v[16:31], v[200:203], v[176:179], v[16:31]
	s_waitcnt lgkmcnt(4)
	v_mfma_f32_32x32x16_bf16 v[0:15], v[208:211], v[176:179], v[0:15]
	s_waitcnt lgkmcnt(2)
	v_mfma_f32_32x32x16_bf16 v[16:31], v[168:171], v[212:215], v[16:31]
	s_waitcnt lgkmcnt(0)
	v_mfma_f32_32x32x16_bf16 v[0:15], v[188:191], v[212:215], v[0:15]
	s_waitcnt vmcnt(1)
	ds_write_b128 v154, v[126:129] offset:13312
	s_and_saveexec_b64 s[6:7], s[38:39]
	v_add3_u32 v126, 0, v151, v136
	ds_write_b128 v126, v[122:125] offset:13440
	s_or_b64 exec, exec, s[6:7]
	v_add_u32_e32 v140, s8, v153
	v_ashrrev_i32_e32 v141, 31, v140
	v_lshlrev_b64 v[126:127], 10, v[140:141]
	v_lshl_add_u64 v[126:127], s[92:93], 0, v[126:127]
	v_lshl_add_u64 v[126:127], v[126:127], 0, s[68:69]
	v_lshl_add_u64 v[126:127], v[126:127], 0, v[98:99]
	s_waitcnt vmcnt(0)
	ds_write_b128 v135, v[130:133] offset:26624
	global_load_dwordx4 v[130:133], v[126:127], off
	s_and_saveexec_b64 s[6:7], s[38:39]
	s_cbranch_execz .LBB0_545
	v_add_u32_e32 v122, s8, v152
	v_ashrrev_i32_e32 v123, 31, v122
	v_lshlrev_b64 v[122:123], 6, v[122:123]
	v_lshl_add_u64 v[122:123], s[26:27], 0, v[122:123]
	v_lshl_add_u64 v[122:123], v[100:101], 1, v[122:123]
	global_load_dwordx4 v[122:125], v[122:123], off

.Lmla_norescale:
	s_add_i32 s10, s1, -1
	s_and_b32 s11, s10, 1
	s_mul_i32 s7, s11, 0x3400
	v_add_u32_e32 v147, s7, v149
	ds_read_b128 v[110:113], v147
	ds_read_b128 v[114:117], v147 offset:32
	ds_read_b128 v[118:121], v147 offset:64
	ds_read_b128 v[152:155], v147 offset:96
	s_and_b32 s6, s1, 1
	v_exp_f32_e32 v141, v48
	v_exp_f32_e32 v157, v49
	v_exp_f32_e32 v158, v50
	v_exp_f32_e32 v159, v51
	v_exp_f32_e32 v160, v52
	v_exp_f32_e32 v161, v53
	v_exp_f32_e32 v162, v54
	v_exp_f32_e32 v163, v55
	v_exp_f32_e32 v164, v56
	v_exp_f32_e32 v165, v57
	v_exp_f32_e32 v166, v58
	v_exp_f32_e32 v167, v59
	v_exp_f32_e32 v168, v60
	v_exp_f32_e32 v169, v61
	v_exp_f32_e32 v170, v62
	v_exp_f32_e32 v171, v63
	s_waitcnt lgkmcnt(3)
	v_mfma_f32_32x32x16_bf16 v[48:63], v[110:113], v[106:109], v[64:79]
	ds_read_b128 v[234:237], v147 offset:128
	v_exp_f32_e32 v172, v32
	v_exp_f32_e32 v173, v33
	v_exp_f32_e32 v174, v34
	s_waitcnt lgkmcnt(3)
	v_mfma_f32_32x32x16_bf16 v[48:63], v[114:117], v[102:105], v[48:63]
	ds_read_b128 v[212:215], v147 offset:160
	v_exp_f32_e32 v175, v35
	v_exp_f32_e32 v176, v36
	v_exp_f32_e32 v177, v37
	s_waitcnt lgkmcnt(3)
	v_mfma_f32_32x32x16_bf16 v[48:63], v[118:121], v[92:95], v[48:63]
	ds_read_b128 v[216:219], v147 offset:6656
	v_exp_f32_e32 v178, v38
	v_exp_f32_e32 v179, v39
	v_exp_f32_e32 v187, v40
	s_waitcnt lgkmcnt(3)
	v_mfma_f32_32x32x16_bf16 v[48:63], v[152:155], v[88:91], v[48:63]
	ds_read_b128 v[238:241], v147 offset:6688
	v_exp_f32_e32 v188, v41
	v_exp_f32_e32 v189, v42
	v_exp_f32_e32 v190, v43
	s_waitcnt lgkmcnt(3)
	v_mfma_f32_32x32x16_bf16 v[48:63], v[234:237], v[84:87], v[48:63]
	ds_read_b128 v[242:245], v147 offset:6720
	v_exp_f32_e32 v191, v44
	v_exp_f32_e32 v192, v45
	v_exp_f32_e32 v193, v46
	s_waitcnt lgkmcnt(3)
	v_mfma_f32_32x32x16_bf16 v[48:63], v[212:215], v[80:83], v[48:63]
	ds_read_b128 v[246:249], v147 offset:6752
	v_exp_f32_e32 v194, v47
	v_cvt_pk_bf16_f32 v196, v141, v157
	v_cvt_pk_bf16_f32 v197, v158, v159
	s_waitcnt lgkmcnt(3)
	v_mfma_f32_32x32x16_bf16 v[32:47], v[216:219], v[106:109], v[64:79]
	ds_read_b128 v[110:113], v147 offset:6784
	v_cvt_pk_bf16_f32 v198, v160, v161
	v_cvt_pk_bf16_f32 v199, v162, v163
	v_cvt_pk_bf16_f32 v200, v164, v165
	v_cvt_pk_bf16_f32 v201, v166, v167
	s_waitcnt lgkmcnt(3)
	v_mfma_f32_32x32x16_bf16 v[32:47], v[238:241], v[102:105], v[32:47]
	ds_read_b128 v[114:117], v147 offset:6816
	v_cvt_pk_bf16_f32 v202, v168, v169
	v_cvt_pk_bf16_f32 v203, v170, v171
	v_cvt_pk_bf16_f32 v204, v172, v173
	v_cvt_pk_bf16_f32 v205, v174, v175
	s_waitcnt lgkmcnt(3)
	v_mfma_f32_32x32x16_bf16 v[32:47], v[242:245], v[92:95], v[32:47]
	s_mul_i32 s7, s6, 0x3000
	v_add_u32_e32 v156, s7, v97
	ds_read_b64_tr_b16 v[118:119], v156 offset:26624
	ds_read_b64_tr_b16 v[120:121], v156 offset:28160
	ds_read_b64_tr_b16 v[154:155], v156 offset:28224
	ds_read_b64_tr_b16 v[152:153], v156 offset:26688
	v_cvt_pk_bf16_f32 v206, v176, v177
	v_cvt_pk_bf16_f32 v207, v178, v179
	v_cvt_pk_bf16_f32 v208, v187, v188
	s_waitcnt lgkmcnt(6)
	v_mfma_f32_32x32x16_bf16 v[32:47], v[246:249], v[88:91], v[32:47]
	ds_read_b64_tr_b16 v[234:235], v156 offset:29696
	ds_read_b64_tr_b16 v[236:237], v156 offset:31232
	ds_read_b64_tr_b16 v[214:215], v156 offset:31296
	ds_read_b64_tr_b16 v[212:213], v156 offset:29760
	v_cvt_pk_bf16_f32 v209, v189, v190
	v_cvt_pk_bf16_f32 v210, v191, v192
	v_cvt_pk_bf16_f32 v211, v193, v194
	v_add_f32_e32 v195, v172, v141
	s_waitcnt lgkmcnt(9)
	v_mfma_f32_32x32x16_bf16 v[32:47], v[110:113], v[84:87], v[32:47]
	ds_read_b64_tr_b16 v[216:217], v156 offset:32768
	ds_read_b64_tr_b16 v[218:219], v156 offset:34304
	ds_read_b64_tr_b16 v[240:241], v156 offset:34368
	ds_read_b64_tr_b16 v[238:239], v156 offset:32832
	v_add_f32_e32 v195, 0, v195
	v_add_f32_e32 v101, v173, v157
	v_add_f32_e32 v195, v101, v195
	v_add_f32_e32 v101, v174, v158
	s_waitcnt lgkmcnt(12)
	v_mfma_f32_32x32x16_bf16 v[32:47], v[114:117], v[80:83], v[32:47]
	ds_read_b64_tr_b16 v[242:243], v156 offset:35840
	ds_read_b64_tr_b16 v[244:245], v156 offset:37376
	ds_read_b64_tr_b16 v[248:249], v156 offset:37440
	ds_read_b64_tr_b16 v[246:247], v156 offset:35904
	v_add_f32_e32 v195, v101, v195
	v_add_f32_e32 v101, v175, v159
	v_add_f32_e32 v195, v101, v195
	s_nop 1
	v_add_f32_e32 v101, v176, v160
	v_add_f32_e32 v195, v101, v195
	v_add_f32_e32 v101, v177, v161
	v_add_f32_e32 v195, v101, v195
	s_waitcnt lgkmcnt(14)
	v_mfma_f32_32x32x16_bf16 v[16:31], v[118:121], v[196:199], v[16:31]
	v_add_f32_e32 v101, v178, v162
	v_add_f32_e32 v195, v101, v195
	v_add_f32_e32 v101, v179, v163
	v_max3_f32 v100, v48, v49, v50
	v_max3_f32 v100, v100, v51, v52
	v_max3_f32 v100, v100, v53, v54
	s_waitcnt lgkmcnt(12)
	v_mfma_f32_32x32x16_bf16 v[0:15], v[152:155], v[196:199], v[0:15]
	s_mulk_i32 s6, 0x3400
	s_add_i32 s12, s6, 0
	v_add3_u32 v156, s12, v150, v134
	s_waitcnt vmcnt(1)
	ds_write_b128 v156, v[130:133]
	s_and_saveexec_b64 s[6:7], s[38:39]
	v_add3_u32 v156, s12, v151, v136
	ds_write_b128 v156, v[122:125] offset:128
	s_or_b64 exec, exec, s[6:7]
	v_add_f32_e32 v195, v101, v195
	v_add_f32_e32 v101, v187, v164
	v_max3_f32 v100, v100, v55, v56
	v_max3_f32 v100, v100, v57, v58
	s_waitcnt lgkmcnt(11)
	v_mfma_f32_32x32x16_bf16 v[16:31], v[234:237], v[200:203], v[16:31]
	v_add_f32_e32 v195, v101, v195
	v_add_f32_e32 v101, v188, v165
	v_add_f32_e32 v195, v101, v195
	v_max3_f32 v100, v100, v59, v60
	v_max3_f32 v100, v100, v61, v62
	v_max3_f32 v100, v100, v63, v63
	s_waitcnt lgkmcnt(9)
	v_mfma_f32_32x32x16_bf16 v[0:15], v[212:215], v[200:203], v[0:15]
	s_mulk_i32 s11, 0x3000
	v_add_u32_e32 v156, s11, v135
	v_add_u32_e32 v228, 64, v140
	s_waitcnt vmcnt(0)
	ds_write_b128 v156, v[126:129] offset:26624
	s_waitcnt lgkmcnt(8)
	v_mfma_f32_32x32x16_bf16 v[16:31], v[216:219], v[204:207], v[16:31]
	v_add_f32_e32 v101, v189, v166
	v_add_f32_e32 v195, v101, v195
	v_add_f32_e32 v101, v190, v167
	v_add_f32_e32 v195, v101, v195
	v_max3_f32 v98, v32, v33, v34
	v_max3_f32 v98, v98, v35, v36
	v_max3_f32 v98, v98, v37, v38
	s_waitcnt lgkmcnt(6)
	v_mfma_f32_32x32x16_bf16 v[0:15], v[238:241], v[204:207], v[0:15]
	s_cmpk_lt_u32 s10, 0x42
	s_cbranch_scc0 .Lmla_noload
	v_ashrrev_i32_e32 v229, 31, v228
	v_lshlrev_b64 v[220:221], 10, v[228:229]
	v_lshl_add_u64 v[220:221], v[142:143], 0, v[220:221]
	global_load_dwordx4 v[130:133], v[220:221], off
	s_and_saveexec_b64 s[6:7], s[38:39]
	s_cbranch_execz .Lmla_norr
	v_ashrrev_i32_e32 v147, 31, v146
	v_lshlrev_b64 v[220:221], 6, v[146:147]
	v_lshl_add_u64 v[220:221], v[144:145], 0, v[220:221]
	global_load_dwordx4 v[122:125], v[220:221], off

.LBB0_561:
	v_exp_f32_e32 v139, v48
	v_exp_f32_e32 v157, v32
	v_exp_f32_e32 v32, v49
	s_waitcnt vmcnt(1)
	v_exp_f32_e32 v122, v33
	v_mov_b32_e32 v33, v99
	v_add_f32_e32 v123, v157, v139
	v_exp_f32_e32 v130, v35
	v_pk_add_f32 v[48:49], v[122:123], v[32:33]
	v_exp_f32_e32 v33, v50
	v_pk_add_f32 v[124:125], v[48:49], v[48:49] op_sel_hi:[0,1]
	v_exp_f32_e32 v49, v34
	v_exp_f32_e32 v124, v51
	v_exp_f32_e32 v52, v52
	v_exp_f32_e32 v123, v36
	v_add_f32_e32 v131, v49, v33
	v_pk_add_f32 v[34:35], v[130:131], v[124:125]
	v_exp_f32_e32 v132, v37
	v_pk_add_f32 v[34:35], v[34:35], v[34:35] op_sel_hi:[0,1]
	v_exp_f32_e32 v34, v53
	v_add_f32_e32 v133, v123, v52
	v_exp_f32_e32 v125, v38
	v_exp_f32_e32 v140, v39
	v_pk_add_f32 v[36:37], v[132:133], v[34:35]
	v_exp_f32_e32 v35, v54
	v_pk_add_f32 v[36:37], v[36:37], v[36:37] op_sel_hi:[0,1]
	v_exp_f32_e32 v36, v55
	v_exp_f32_e32 v131, v40
	v_add_f32_e32 v141, v125, v35
	v_exp_f32_e32 v142, v41
	v_pk_add_f32 v[38:39], v[140:141], v[36:37]
	v_exp_f32_e32 v37, v56
	v_pk_add_f32 v[38:39], v[38:39], v[38:39] op_sel_hi:[0,1]
	v_exp_f32_e32 v38, v57
	v_exp_f32_e32 v133, v42
	v_add_f32_e32 v143, v131, v37
	v_exp_f32_e32 v144, v43
	v_pk_add_f32 v[40:41], v[142:143], v[38:39]
	v_exp_f32_e32 v39, v58
	v_pk_add_f32 v[40:41], v[40:41], v[40:41] op_sel_hi:[0,1]
	v_exp_f32_e32 v40, v59
	v_exp_f32_e32 v141, v44
	v_add_f32_e32 v145, v133, v39
	v_exp_f32_e32 v146, v45
	v_pk_add_f32 v[42:43], v[144:145], v[40:41]
	v_exp_f32_e32 v41, v60
	v_pk_add_f32 v[42:43], v[42:43], v[42:43] op_sel_hi:[0,1]
	v_exp_f32_e32 v42, v61
	v_exp_f32_e32 v158, v47
	v_add_f32_e32 v147, v141, v41
	v_cvt_pk_bf16_f32 v50, v139, v32
	v_pk_add_f32 v[44:45], v[146:147], v[42:43]
	v_exp_f32_e32 v43, v62
	v_pk_add_f32 v[44:45], v[44:45], v[44:45] op_sel_hi:[0,1]
	v_exp_f32_e32 v62, v46
	v_exp_f32_e32 v44, v63
	v_cvt_pk_bf16_f32 v51, v33, v124
	v_cvt_pk_bf16_f32 v58, v157, v122
	v_add_f32_e32 v159, v62, v43
	v_pk_add_f32 v[46:47], v[158:159], v[44:45]
	v_cvt_pk_bf16_f32 v59, v49, v130
	v_add_f32_e32 v45, v46, v47
	v_add_f32_e32 v48, v138, v45
	v_cvt_pk_bf16_f32 v60, v123, v132
	v_cvt_pk_bf16_f32 v61, v125, v140
	v_cvt_pk_bf16_f32 v122, v131, v142
	v_cvt_pk_bf16_f32 v123, v133, v144
	v_cvt_pk_bf16_f32 v124, v141, v146
	v_cvt_pk_bf16_f32 v125, v62, v158
	ds_read_b128 v[130:133], v149 offset:19968
	ds_read_b128 v[138:141], v149 offset:13312
	ds_read_b128 v[142:145], v149 offset:13344
	ds_read_b128 v[158:161], v149 offset:20000
	ds_read_b128 v[162:165], v149 offset:13376
	ds_read_b128 v[166:169], v149 offset:20032
	v_mov_b32_e32 v65, v64
	v_mov_b32_e32 v66, v64
	v_mov_b32_e32 v67, v64
	v_mov_b32_e32 v68, v64
	v_mov_b32_e32 v69, v64
	v_mov_b32_e32 v70, v64
	v_mov_b32_e32 v71, v64
	v_mov_b32_e32 v72, v64
	v_mov_b32_e32 v73, v64
	v_mov_b32_e32 v74, v64
	v_mov_b32_e32 v75, v64
	v_mov_b32_e32 v76, v64
	v_mov_b32_e32 v77, v64
	v_mov_b32_e32 v78, v64
	v_mov_b32_e32 v79, v64
	v_cvt_pk_bf16_f32 v52, v52, v34
	v_cvt_pk_bf16_f32 v53, v35, v36
	v_cvt_pk_bf16_f32 v54, v37, v38
	v_cvt_pk_bf16_f32 v55, v39, v40
	v_cvt_pk_bf16_f32 v56, v41, v42
	v_cvt_pk_bf16_f32 v57, v43, v44
	s_waitcnt lgkmcnt(4)
	v_mfma_f32_32x32x16_bf16 v[32:47], v[138:141], v[106:109], v[64:79]
	v_mfma_f32_32x32x16_bf16 v[64:79], v[130:133], v[106:109], v[64:79]
	ds_read_b128 v[130:133], v149 offset:13408
	ds_read_b128 v[138:141], v149 offset:20064
	s_waitcnt lgkmcnt(5)
	v_mfma_f32_32x32x16_bf16 v[32:47], v[142:145], v[102:105], v[32:47]
	s_waitcnt lgkmcnt(4)
	v_mfma_f32_32x32x16_bf16 v[64:79], v[158:161], v[102:105], v[64:79]
	ds_read_b128 v[142:145], v149 offset:13440
	ds_read_b128 v[158:161], v149 offset:20096
	s_waitcnt lgkmcnt(5)
	v_mfma_f32_32x32x16_bf16 v[32:47], v[162:165], v[92:95], v[32:47]
	s_waitcnt lgkmcnt(4)
	v_mfma_f32_32x32x16_bf16 v[64:79], v[166:169], v[92:95], v[64:79]
	ds_read_b128 v[162:165], v149 offset:13472
	ds_read_b128 v[166:169], v149 offset:20128
	s_waitcnt lgkmcnt(5)
	v_mfma_f32_32x32x16_bf16 v[32:47], v[130:133], v[88:91], v[32:47]
	s_waitcnt lgkmcnt(4)
	v_mfma_f32_32x32x16_bf16 v[64:79], v[138:141], v[88:91], v[64:79]
	ds_read_b64_tr_b16 v[130:131], v97 offset:26624
	ds_read_b64_tr_b16 v[132:133], v97 offset:28160
	ds_read_b64_tr_b16 v[140:141], v97 offset:28224
	ds_read_b64_tr_b16 v[138:139], v97 offset:26688
	s_waitcnt lgkmcnt(7)
	v_mfma_f32_32x32x16_bf16 v[32:47], v[142:145], v[84:87], v[32:47]
	s_waitcnt lgkmcnt(6)
	v_mfma_f32_32x32x16_bf16 v[64:79], v[158:161], v[84:87], v[64:79]
	ds_read_b64_tr_b16 v[142:143], v97 offset:29696
	ds_read_b64_tr_b16 v[144:145], v97 offset:31232
	ds_read_b64_tr_b16 v[160:161], v97 offset:31296
	ds_read_b64_tr_b16 v[158:159], v97 offset:29760
	s_waitcnt lgkmcnt(9)
	v_mfma_f32_32x32x16_bf16 v[32:47], v[162:165], v[80:83], v[32:47]
	s_waitcnt lgkmcnt(8)
	v_mfma_f32_32x32x16_bf16 v[64:79], v[166:169], v[80:83], v[64:79]
	ds_read_b64_tr_b16 v[162:163], v97 offset:32768
	ds_read_b64_tr_b16 v[164:165], v97 offset:34304
	ds_read_b64_tr_b16 v[168:169], v97 offset:34368
	ds_read_b64_tr_b16 v[166:167], v97 offset:32832
	s_waitcnt lgkmcnt(10)
	v_mfma_f32_32x32x16_bf16 v[16:31], v[130:133], v[50:53], v[16:31]
	s_waitcnt lgkmcnt(8)
	v_mfma_f32_32x32x16_bf16 v[0:15], v[138:141], v[50:53], v[0:15]
	ds_read_b64_tr_b16 v[50:51], v97 offset:35840
	ds_read_b64_tr_b16 v[52:53], v97 offset:37376
	ds_read_b64_tr_b16 v[132:133], v97 offset:37440
	ds_read_b64_tr_b16 v[130:131], v97 offset:35904
	s_waitcnt lgkmcnt(10)
	v_mfma_f32_32x32x16_bf16 v[16:31], v[142:145], v[54:57], v[16:31]
	s_waitcnt lgkmcnt(8)
	v_mfma_f32_32x32x16_bf16 v[0:15], v[158:161], v[54:57], v[0:15]
	s_waitcnt lgkmcnt(6)
	v_mfma_f32_32x32x16_bf16 v[16:31], v[162:165], v[58:61], v[16:31]
	s_waitcnt lgkmcnt(4)
	v_mfma_f32_32x32x16_bf16 v[0:15], v[166:169], v[58:61], v[0:15]
	s_waitcnt lgkmcnt(2)
	v_mfma_f32_32x32x16_bf16 v[16:31], v[50:53], v[122:125], v[16:31]
	s_waitcnt lgkmcnt(0)
	v_mfma_f32_32x32x16_bf16 v[0:15], v[130:133], v[122:125], v[0:15]
	v_max3_f32 v49, v32, v33, v64
	v_max3_f32 v50, v34, v35, v65
	s_waitcnt vmcnt(0)
	ds_write_b128 v135, v[126:129] offset:38912
	v_max3_f32 v49, v49, v66, v67
	v_max3_f32 v50, v50, v38, v39
	s_waitcnt lgkmcnt(0)
	s_barrier
	s_nop 0
	v_max3_f32 v49, v49, v36, v37
	v_max3_f32 v50, v50, v70, v71
	s_nop 0
	v_max3_f32 v49, v49, v68, v69
	v_max3_f32 v50, v50, v42, v43
	s_nop 0
	v_max3_f32 v49, v49, v40, v41
	v_max3_f32 v50, v50, v74, v75
	s_nop 0
	v_max3_f32 v49, v49, v72, v73
	v_max3_f32 v50, v50, v46, v47
	s_nop 0
	v_max3_f32 v49, v49, v44, v45
	v_max3_f32 v50, v50, v78, v79
	s_nop 0
	v_max3_f32 v49, v49, v76, v77
	s_nop 0
	v_max3_f32 v49, v49, v50, v50
	ds_bpermute_b32 v50, v137, v49
	s_waitcnt lgkmcnt(0)
	v_max3_f32 v49, v49, v50, v49
	s_nop 0
	v_cmp_lt_f32_e32 vcc, s78, v49
	s_cbranch_vccz .LBB0_563
	v_max_f32_e32 v49, v49, v49
	v_max_f32_e32 v50, 0, v49
	v_exp_f32_e64 v52, -v50
	v_pk_add_f32 v[32:33], v[32:33], v[50:51] op_sel_hi:[1,0] neg_lo:[0,1] neg_hi:[0,1]
	v_pk_add_f32 v[64:65], v[64:65], v[50:51] op_sel_hi:[1,0] neg_lo:[0,1] neg_hi:[0,1]
	v_pk_add_f32 v[34:35], v[34:35], v[50:51] op_sel_hi:[1,0] neg_lo:[0,1] neg_hi:[0,1]
	v_mul_f32_e32 v48, v48, v52
	v_pk_add_f32 v[66:67], v[66:67], v[50:51] op_sel_hi:[1,0] neg_lo:[0,1] neg_hi:[0,1]
	v_pk_add_f32 v[36:37], v[36:37], v[50:51] op_sel_hi:[1,0] neg_lo:[0,1] neg_hi:[0,1]
	v_pk_add_f32 v[68:69], v[68:69], v[50:51] op_sel_hi:[1,0] neg_lo:[0,1] neg_hi:[0,1]
	v_pk_add_f32 v[38:39], v[38:39], v[50:51] op_sel_hi:[1,0] neg_lo:[0,1] neg_hi:[0,1]
	v_pk_add_f32 v[70:71], v[70:71], v[50:51] op_sel_hi:[1,0] neg_lo:[0,1] neg_hi:[0,1]
	v_pk_add_f32 v[40:41], v[40:41], v[50:51] op_sel_hi:[1,0] neg_lo:[0,1] neg_hi:[0,1]
	v_pk_add_f32 v[72:73], v[72:73], v[50:51] op_sel_hi:[1,0] neg_lo:[0,1] neg_hi:[0,1]
	v_pk_add_f32 v[42:43], v[42:43], v[50:51] op_sel_hi:[1,0] neg_lo:[0,1] neg_hi:[0,1]
	v_pk_add_f32 v[74:75], v[74:75], v[50:51] op_sel_hi:[1,0] neg_lo:[0,1] neg_hi:[0,1]
	v_pk_add_f32 v[44:45], v[44:45], v[50:51] op_sel_hi:[1,0] neg_lo:[0,1] neg_hi:[0,1]
	v_pk_add_f32 v[76:77], v[76:77], v[50:51] op_sel_hi:[1,0] neg_lo:[0,1] neg_hi:[0,1]
	v_pk_add_f32 v[46:47], v[46:47], v[50:51] op_sel_hi:[1,0] neg_lo:[0,1] neg_hi:[0,1]
	v_pk_add_f32 v[78:79], v[78:79], v[50:51] op_sel_hi:[1,0] neg_lo:[0,1] neg_hi:[0,1]
	v_pk_mul_f32 v[30:31], v[30:31], v[52:53] op_sel_hi:[1,0]
	v_pk_mul_f32 v[28:29], v[28:29], v[52:53] op_sel_hi:[1,0]
	v_pk_mul_f32 v[26:27], v[26:27], v[52:53] op_sel_hi:[1,0]
	v_pk_mul_f32 v[24:25], v[24:25], v[52:53] op_sel_hi:[1,0]
	v_pk_mul_f32 v[22:23], v[22:23], v[52:53] op_sel_hi:[1,0]
	v_pk_mul_f32 v[20:21], v[20:21], v[52:53] op_sel_hi:[1,0]
	v_pk_mul_f32 v[18:19], v[18:19], v[52:53] op_sel_hi:[1,0]
	v_pk_mul_f32 v[16:17], v[16:17], v[52:53] op_sel_hi:[1,0]
	v_pk_mul_f32 v[14:15], v[14:15], v[52:53] op_sel_hi:[1,0]
	v_pk_mul_f32 v[12:13], v[12:13], v[52:53] op_sel_hi:[1,0]
	v_pk_mul_f32 v[10:11], v[10:11], v[52:53] op_sel_hi:[1,0]
	v_pk_mul_f32 v[8:9], v[8:9], v[52:53] op_sel_hi:[1,0]
	v_pk_mul_f32 v[6:7], v[6:7], v[52:53] op_sel_hi:[1,0]
	v_pk_mul_f32 v[4:5], v[4:5], v[52:53] op_sel_hi:[1,0]
	v_pk_mul_f32 v[2:3], v[2:3], v[52:53] op_sel_hi:[1,0]
	v_pk_mul_f32 v[0:1], v[0:1], v[52:53] op_sel_hi:[1,0]
.LBB0_563:
	v_exp_f32_e32 v49, v32
	v_exp_f32_e32 v122, v64
	v_exp_f32_e32 v50, v33
	v_exp_f32_e32 v52, v65
	v_mov_b32_e32 v51, v99
	v_add_f32_e32 v53, v122, v49
	v_exp_f32_e32 v56, v67
	v_pk_add_f32 v[32:33], v[52:53], v[50:51]
	v_exp_f32_e32 v51, v34
	v_pk_add_f32 v[54:55], v[32:33], v[32:33] op_sel_hi:[0,1]
	v_exp_f32_e32 v53, v66
	v_exp_f32_e32 v54, v35
	v_exp_f32_e32 v36, v36
	v_exp_f32_e32 v60, v69
	v_add_f32_e32 v57, v53, v51
	v_pk_add_f32 v[32:33], v[56:57], v[54:55]
	v_exp_f32_e32 v55, v68
	v_pk_add_f32 v[58:59], v[32:33], v[32:33] op_sel_hi:[0,1]
	v_exp_f32_e32 v58, v37
	v_exp_f32_e32 v37, v38
	v_add_f32_e32 v61, v55, v36
	v_exp_f32_e32 v57, v70
	v_pk_add_f32 v[32:33], v[60:61], v[58:59]
	v_exp_f32_e32 v64, v71
	v_pk_add_f32 v[62:63], v[32:33], v[32:33] op_sel_hi:[0,1]
	v_exp_f32_e32 v62, v39
	v_add_f32_e32 v65, v57, v37
	v_exp_f32_e32 v59, v40
	v_exp_f32_e32 v61, v72
	v_pk_add_f32 v[32:33], v[64:65], v[62:63]
	v_exp_f32_e32 v66, v73
	v_pk_add_f32 v[38:39], v[32:33], v[32:33] op_sel_hi:[0,1]
	v_exp_f32_e32 v38, v41
	v_add_f32_e32 v67, v61, v59
	v_exp_f32_e32 v63, v74
	v_exp_f32_e32 v68, v75
	v_pk_add_f32 v[32:33], v[66:67], v[38:39]
	v_exp_f32_e32 v39, v42
	v_pk_add_f32 v[40:41], v[32:33], v[32:33] op_sel_hi:[0,1]
	v_exp_f32_e32 v40, v43
	v_exp_f32_e32 v65, v76
	v_add_f32_e32 v69, v63, v39
	v_exp_f32_e32 v70, v77
	v_pk_add_f32 v[32:33], v[68:69], v[40:41]
	v_exp_f32_e32 v41, v44
	v_pk_add_f32 v[42:43], v[32:33], v[32:33] op_sel_hi:[0,1]
	v_exp_f32_e32 v42, v45
	v_exp_f32_e32 v67, v78
	v_add_f32_e32 v71, v65, v41
	v_exp_f32_e32 v72, v79
	v_pk_add_f32 v[32:33], v[70:71], v[42:43]
	v_exp_f32_e32 v43, v46
	v_pk_add_f32 v[44:45], v[32:33], v[32:33] op_sel_hi:[0,1]
	v_exp_f32_e32 v44, v47
	v_cvt_pk_bf16_f32 v34, v49, v50
	v_add_f32_e32 v73, v67, v43
	v_cvt_pk_bf16_f32 v35, v51, v54
	v_pk_add_f32 v[32:33], v[72:73], v[44:45]
	v_cvt_pk_bf16_f32 v36, v36, v58
	v_add_f32_e32 v32, v32, v33
	v_add_f32_e32 v32, v48, v32
	v_cvt_pk_bf16_f32 v37, v37, v62
	v_cvt_pk_bf16_f32 v38, v59, v38
	v_cvt_pk_bf16_f32 v39, v39, v40
	v_cvt_pk_bf16_f32 v40, v41, v42
	v_cvt_pk_bf16_f32 v41, v43, v44
	v_cvt_pk_bf16_f32 v42, v122, v52
	v_cvt_pk_bf16_f32 v43, v53, v56
	v_cvt_pk_bf16_f32 v44, v55, v60
	v_cvt_pk_bf16_f32 v45, v57, v64
	v_cvt_pk_bf16_f32 v46, v61, v66
	v_cvt_pk_bf16_f32 v47, v63, v68
	v_cvt_pk_bf16_f32 v48, v65, v70
	v_cvt_pk_bf16_f32 v49, v67, v72
	ds_read_b64_tr_b16 v[50:51], v97 offset:38912
	ds_read_b64_tr_b16 v[52:53], v97 offset:40448
	ds_read_b64_tr_b16 v[56:57], v97 offset:40512
	ds_read_b64_tr_b16 v[54:55], v97 offset:38976
	ds_read_b64_tr_b16 v[58:59], v97 offset:41984
	ds_read_b64_tr_b16 v[60:61], v97 offset:43520
	ds_read_b64_tr_b16 v[64:65], v97 offset:43584
	ds_read_b64_tr_b16 v[62:63], v97 offset:42048
	ds_read_b64_tr_b16 v[66:67], v97 offset:45056
	ds_read_b64_tr_b16 v[68:69], v97 offset:46592
	ds_read_b64_tr_b16 v[72:73], v97 offset:46656
	ds_read_b64_tr_b16 v[70:71], v97 offset:45120
	s_waitcnt lgkmcnt(10)
	v_mfma_f32_32x32x16_bf16 v[16:31], v[50:53], v[34:37], v[16:31]
	s_waitcnt lgkmcnt(8)
	v_mfma_f32_32x32x16_bf16 v[0:15], v[54:57], v[34:37], v[0:15]
	ds_read_b64_tr_b16 v[34:35], v97 offset:48128
	ds_read_b64_tr_b16 v[36:37], v97 offset:49664
	ds_read_b64_tr_b16 v[52:53], v97 offset:49728
	ds_read_b64_tr_b16 v[50:51], v97 offset:48192
	s_waitcnt lgkmcnt(10)
	v_mfma_f32_32x32x16_bf16 v[16:31], v[58:61], v[38:41], v[16:31]
	s_waitcnt lgkmcnt(8)
	v_mfma_f32_32x32x16_bf16 v[0:15], v[62:65], v[38:41], v[0:15]
	s_waitcnt lgkmcnt(6)
	v_mfma_f32_32x32x16_bf16 v[16:31], v[66:69], v[42:45], v[16:31]
	s_waitcnt lgkmcnt(4)
	v_mfma_f32_32x32x16_bf16 v[0:15], v[70:73], v[42:45], v[0:15]
	s_waitcnt lgkmcnt(2)
	v_mfma_f32_32x32x16_bf16 v[16:31], v[34:37], v[46:49], v[16:31]
	s_waitcnt lgkmcnt(0)
	v_mfma_f32_32x32x16_bf16 v[0:15], v[50:53], v[46:49], v[0:15]
	s_mov_b64 s[6:7], 0
